# v21_g2nodrain
# speedup vs baseline: 1.0129x; 1.0010x over previous
; #define BAR __builtin_amdgcn_s_barrier()
;   const int tid_ = get_tid();
;   const __amdgpu_buffer_rsrc_t A = __builtin_amdgcn_make_buffer_rsrc((void*)Ap, (short)0, 0x7fffffff, 0x00020000);
;   const __amdgpu_buffer_rsrc_t Bt = __builtin_amdgcn_make_buffer_rsrc((void*)Btp, (short)0, 0x7fffffff, 0x00020000);
;   int voff0, voff1;
;   { int r_, c_; stage_rc(tid_ * 16, r_, c_); voff0 = (r_ * K + c_) * 2; stage_rc(tid_ * 16 + 8192, r_, c_); voff1 = (r_ * K + c_) * 2; }
;   const int wid = tid_ >> 6, lane = tid_ & 63, wr = wid >> 2, wc = wid & 3, fr = lane & 15, fq = lane >> 4;
;   bf16x8 At[4][2], B0[2][2], B1[2][2];
;   const int nt = K / BK;
; #pragma unroll
;   for (int a = 0; a < 2; ++a)
; #pragma unroll
;     for (int b = 0; b < 2; ++b)
; #pragma unroll
;       for (int m = 0; m < 4; ++m)
; #pragma unroll
;         for (int n = 0; n < 2; ++n) acc[a][b][m][n] = f32x4{0.f, 0.f, 0.f, 0.f};
;   if (!pre) {
;     STAGE(SB(0, 0), Bt, bcol, 0); STAGE(SA(0, 0), A, brow, 0);
;     STAGE(SB(0, 1), Bt, bcol + HALF, 0); STAGE(SA(0, 1), A, brow + HALF, 0);
;   }
;   if (wr == 1) BAR;
; DEVI void phase_g2(const Params& p, int l) {
;     ...
;     for (int nb = 0; nb < 3; ++nb) {
;       f32x4 acc[2][2][4][2];
;       const u16* A = p.wt_br + (long)(l * 3 + nb) * 2048 * 1024;
;       const u16* Bt = p.ys + (long)nb * T_ * 1024;
;       gemm_core(A, Bt, 1024, brow, bcol, acc);
.LBB0_438:
	s_mul_i32 s2, s94, 3
	s_add_i32 s2, s41, s2
	s_ashr_i32 s3, s2, 31
	s_lshl_b64 s[4:5], s[2:3], 22
	s_add_u32 s8, s23, s4
	v_mov_b32_e32 v0, v234
	s_addc_u32 s4, s24, s5
	s_lshl_b32 s5, s41, 24
	s_add_u32 s88, s14, s5
	v_lshlrev_b32_e32 v1, 4, v0
	v_lshrrev_b32_e32 v3, 3, v0
	v_bfe_u32 v4, v0, 2, 4
	v_and_b32_e32 v2, 32, v0
	v_and_or_b32 v3, v3, 48, v4
	v_add_u32_e32 v134, s33, v1
	s_addc_u32 s5, s15, 0
	s_and_b32 s9, s4, 0xffff
	v_bitop3_b32 v2, v1, v2, 48 bitop3:0x6c
	v_and_b32_e32 v4, 64, v0
	v_lshlrev_b32_e32 v3, 11, v3
	v_readfirstlane_b32 s4, v134
	v_add_u32_e32 v135, 0x2000, v134
	v_or3_b32 v131, v4, v2, v3
	s_and_b32 s89, s5, 0xffff
	s_mov_b32 m0, s4
	v_readfirstlane_b32 s4, v135
	v_add_u32_e32 v136, 0, v1
	v_or_b32_e32 v133, 0x20000, v131
	buffer_load_dwordx4 v131, s[88:91], s30 offen lds
	s_mov_b32 m0, s4
	v_readfirstlane_b32 s4, v136
	v_add_u32_e32 v137, 0x2000, v136
	s_mov_b32 s10, s90
	s_mov_b32 s11, s91
	buffer_load_dwordx4 v133, s[88:91], s30 offen lds
	s_mov_b32 m0, s4
	v_readfirstlane_b32 s4, v137
	v_add_u32_e32 v138, s0, v1
	buffer_load_dwordx4 v131, s[8:11], s31 offen lds
	s_mov_b32 m0, s4
	v_readfirstlane_b32 s4, v138
	v_add_u32_e32 v139, 0x2000, v138
	buffer_load_dwordx4 v133, s[8:11], s31 offen lds
	s_mov_b32 m0, s4
	v_readfirstlane_b32 s4, v139
	v_add_u32_e32 v140, 0x4000, v136
	buffer_load_dwordx4 v131, s[88:91], s34 offen lds
	s_mov_b32 m0, s4
	v_readfirstlane_b32 s4, v140
	v_add_u32_e32 v141, 0x6000, v136
	buffer_load_dwordx4 v133, s[88:91], s34 offen lds
	s_mov_b32 m0, s4
	v_readfirstlane_b32 s4, v141
	buffer_load_dwordx4 v131, s[8:11], s35 offen lds
	s_mov_b32 m0, s4
	v_cmp_gt_u32_e32 vcc, s56, v0
	buffer_load_dwordx4 v133, s[8:11], s35 offen lds
	v_cmp_lt_u32_e64 s[4:5], s80, v0
	s_and_saveexec_b64 s[10:11], s[4:5]
	s_cbranch_execz .LBB0_440
	s_barrier
